# plus chunk-prep conv weights loaded at the top of each item with counted waits per part (wave 0 no longer waits for the v rows before its decay scan)
# speedup vs baseline: 1.0203x; 1.0001x over previous
; #define LAS __attribute__((address_space(3)))
; __device__ __forceinline__ int fresh_tid() { int t = threadIdx.x; asm volatile("" : "+v"(t)); return t; }
; __device__ __forceinline__ void gdn_all(LAS unsigned char* lds, const XcdBarrier& xbar, const int G, const int bx, unsigned char* ws, float* out, const bf16_t* qkv, const float* bg, const float* gconv_w, ...
;     const int nfull = NITEM_P / G, nlate = NITEM_P - nfull * G;
;     unsigned* late_cnt = (unsigned*)(ws + WS_CTL) + 8192 + 1024;
;     {
;         { PrepRaw R; if (nfull > 0) gdn_prep_load(R, bx, 0, qkv, bg, fresh_tid());
;           for (int k = 0; k < nfull; ++k) { const int item = bx + k * G; gdn_prep_item(lds, item, 0, R, k + 1 < nfull ? item + G : -1, qkv, bg, gconv_w, gdn_rec(ws, out, item), gtarr); } }
.LBB0_461:
.LBB0_462:
	v_readlane_b32 s16, v245, 19
	v_readlane_b32 s30, v245, 33
	v_readlane_b32 s31, v245, 34
	s_add_u32 s58, s30, 0x20000
	s_addc_u32 s57, s31, 0
	s_andn2_b64 vcc, exec, s[14:15]
	v_mbcnt_lo_u32_b32 v220, -1, 0
	v_readlane_b32 s17, v245, 20
	v_readlane_b32 s18, v245, 21
	v_readlane_b32 s19, v245, 22
	v_readlane_b32 s20, v245, 23
	v_readlane_b32 s21, v245, 24
	v_readlane_b32 s22, v245, 25
	v_readlane_b32 s23, v245, 26
	v_readlane_b32 s24, v245, 27
	v_readlane_b32 s25, v245, 28
	v_readlane_b32 s26, v245, 29
	v_readlane_b32 s27, v245, 30
	v_readlane_b32 s28, v245, 31
	v_readlane_b32 s29, v245, 32
	s_cbranch_vccnz .LBB0_553
	v_mbcnt_hi_u32_b32 v1, -1, v220
	v_bfrev_b32_e32 v36, 0.5
	s_mov_b32 s15, 0
	v_mov_b32_e32 v34, 0
	s_movk_i32 s2, 0x1800
	s_movk_i32 s17, 0x1100
	s_add_i32 s22, 0, 0x15c00
	s_movk_i32 s23, 0x88
	s_mov_b32 s16, 0x358637bd
	s_mov_b32 s24, 0x800000
	s_add_i32 s25, 0, 0x11800
	s_movk_i32 s26, 0x110
	s_add_i32 s27, 0, 0x1c400
	s_movk_i32 s28, 0x48
	v_lshl_or_b32 v106, v1, 2, v36
	v_mov_b32_e32 v107, 0x110
	v_mov_b32_e32 v108, 0x198
	v_mov_b32_e32 v109, 0x880
	v_mov_b32_e32 v110, 0x908
	v_mov_b32_e32 v111, 0x990
	v_mov_b32_e32 v112, 0xa18
	s_mov_b32 s29, 0
	s_waitcnt vmcnt(0)
	s_branch .LBB0_465

; __device__ __forceinline__ void gdn_prep_item(LAS unsigned char* lds, int item, int b0, PrepRaw& R, int next_item, const bf16_t* qkv, const float* bg, const float* gconv_w, unsigned char* rec, float* gtarr) {
;     ...
;     { const int c = (item >> 3) % NCHUNK, b = b0 + (item >> 3) / NCHUNK, tbase = 64 * c - 48, cc = tid & 15, i0 = (tid >> 4) * 2;
; #pragma unroll
;       for (int j = 0; j < 5; ++j) { const int t = tbase + i0 - 3 + j; xv[j] = (t >= 0) ? *(const u32x4*)(qkv + (size_t)(b * LP + t) * CONVCH + 2048 + h * 128 + 8 * cc) : (u32x4){0u, 0u, 0u, 0u}; } }
;     ...
;                 if (j < 4) { const f32x4 wa = *(const f32x4*)(gconv_w + j * CONVCH + col), wb = *(const f32x4*)(gconv_w + j * CONVCH + col + 4);
; #pragma unroll
;                     for (int e = 0; e < 8; ++e) y0[e] += (e < 4 ? wa[e] : wb[e - 4]) * x[e]; }
;                 if (j > 0) { const f32x4 wa = *(const f32x4*)(gconv_w + (j - 1) * CONVCH + col), wb = *(const f32x4*)(gconv_w + (j - 1) * CONVCH + col + 4);
.LBB0_465:
	s_mul_i32 s0, s29, s96
	s_add_i32 s18, s0, s94
	s_mov_b32 s99, s18
	s_and_b32 s100, s18, 7
	s_lshr_b32 s101, s18, 3
	s_and_b32 s98, s101, 7
	s_lshr_b32 s101, s101, 3
	s_mul_i32 s98, s98, 33
	s_add_i32 s98, s98, s101
	s_lshl_b32 s98, s98, 3
	s_or_b32 s18, s98, s100
	s_ashr_i32 s0, s18, 3
	s_mul_hi_i32 s1, s0, 0x3e0f83e1
	v_mov_b32_e32 v116, v0
	s_lshr_b32 s4, s1, 31
	s_ashr_i32 s1, s1, 3
	s_add_i32 s4, s1, s4
	v_ashrrev_i32_e32 v115, 3, v116
	s_mul_i32 s1, s4, 33
	v_and_b32_e32 v95, -2, v115
	v_and_b32_e32 v114, 15, v116
	s_sub_i32 s0, s0, s1
	v_subrev_u32_e32 v119, 51, v95
	v_ashrrev_i32_e32 v117, 6, v116
	v_lshl_add_u32 v66, s0, 6, v119
	s_lshl_b32 s0, s18, 7
	v_lshlrev_b32_e32 v94, 3, v114
	v_readfirstlane_b32 s30, v117
	s_mulk_i32 s4, 0x810
	s_and_b32 s6, s0, 0x380
	v_or_b32_e32 v132, s6, v94
	v_lshlrev_b32_e32 v132, 2, v132
	v_add_u32_e32 v133, 0x3000, v132
	v_add_u32_e32 v134, 0x6000, v132
	v_add_u32_e32 v135, 0x9000, v132
	v_add_u32_e32 v136, 0x1000, v132
	v_add_u32_e32 v137, 0x4000, v132
	v_add_u32_e32 v138, 0x7000, v132
	v_add_u32_e32 v139, 0xa000, v132
	v_add_u32_e32 v140, 0x2000, v132
	v_add_u32_e32 v141, 0x5000, v132
	v_add_u32_e32 v142, 0x8000, v132
	v_add_u32_e32 v143, 0xb000, v132
	global_load_dwordx4 v[82:85], v132, s[72:73] offset:16
	global_load_dwordx4 v[166:169], v132, s[72:73]
	global_load_dwordx4 v[86:89], v133, s[72:73] offset:16
	global_load_dwordx4 v[90:93], v134, s[72:73] offset:16
	global_load_dwordx4 v[120:123], v135, s[72:73] offset:16
	global_load_dwordx4 v[70:73], v133, s[72:73]
	global_load_dwordx4 v[74:77], v134, s[72:73]
	global_load_dwordx4 v[78:81], v135, s[72:73]
	global_load_dwordx4 v[170:173], v136, s[72:73] offset:16
	global_load_dwordx4 v[174:177], v136, s[72:73]
	global_load_dwordx4 v[178:181], v137, s[72:73] offset:16
	global_load_dwordx4 v[182:185], v137, s[72:73]
	global_load_dwordx4 v[186:189], v138, s[72:73] offset:16
	global_load_dwordx4 v[190:193], v138, s[72:73]
	global_load_dwordx4 v[194:197], v139, s[72:73] offset:16
	global_load_dwordx4 v[198:201], v139, s[72:73]
	global_load_dwordx4 v[202:205], v140, s[72:73]
	global_load_dwordx4 v[206:209], v141, s[72:73]
	global_load_dwordx4 v[210:213], v142, s[72:73]
	global_load_dwordx4 v[214:217], v143, s[72:73]
	global_load_dwordx4 v[222:225], v140, s[72:73] offset:16
	global_load_dwordx4 v[226:229], v141, s[72:73] offset:16
	global_load_dwordx4 v[230:233], v142, s[72:73] offset:16
	global_load_dwordx4 v[234:237], v143, s[72:73] offset:16
	v_cmp_lt_i32_e32 vcc, -1, v66
	v_lshlrev_b32_e32 v36, 1, v94
	v_mov_b32_e32 v46, 0
	v_mov_b32_e32 v47, 0
	v_mov_b32_e32 v48, 0
	v_mov_b32_e32 v49, 0
	s_and_saveexec_b64 s[0:1], vcc
	s_cbranch_execz .LBB0_467
	v_add_u32_e32 v37, s4, v66
	v_mov_b64_e32 v[46:47], s[88:89]
	v_mad_i64_i32 v[46:47], s[8:9], v37, s2, v[46:47]
	s_lshl_b32 s14, s6, 1
	v_lshl_add_u64 v[46:47], v[46:47], 0, s[14:15]
	v_mov_b32_e32 v37, v34
	v_lshl_add_u64 v[46:47], v[46:47], 0, v[36:37]
	v_add_co_u32_e32 v46, vcc, 0x1000, v46
	s_nop 1
	v_addc_co_u32_e32 v47, vcc, 0, v47, vcc
	global_load_dwordx4 v[46:49], v[46:47], off

; __device__ __forceinline__ void gdn_prep_item(LAS unsigned char* lds, int item, int b0, PrepRaw& R, int next_item, const bf16_t* qkv, const float* bg, const float* gconv_w, unsigned char* rec, float* gtarr) {
;     ...
;     if (wave == 0) {
;         float G = R.gi;
; #pragma unroll
;         for (int o = 1; o < 64; o <<= 1) { const float v = __shfl_up(G, o); if (lane >= o) G += v; }
;         const float Gl = __shfl(G, 63);
;         Gs[lane] = G; Bs[lane] = R.be; EG[lane] = __expf(G); DKs[lane] = __expf(Gl - G);
;         if (lane == 0) gtarr[item] = __expf(Gl);
;     }
.LBB0_477:
	v_and_b32_e32 v36, 64, v1
	v_add_u32_e32 v37, -1, v1
	v_cmp_lt_i32_e32 vcc, v37, v36
	v_add_u32_e32 v66, -2, v1
	v_cmp_lt_i32_e64 s[0:1], v66, v36
	v_cndmask_b32_e32 v37, v37, v1, vcc
	v_lshlrev_b32_e32 v37, 2, v37
	s_waitcnt vmcnt(36)
	ds_bpermute_b32 v37, v37, v113
	v_cmp_eq_u32_e32 vcc, 0, v118
	v_cndmask_b32_e64 v66, v66, v1, s[0:1]
	v_lshlrev_b32_e32 v66, 2, v66
	v_add_u32_e32 v67, -4, v1
	s_waitcnt lgkmcnt(0)
	v_add_f32_e32 v37, v113, v37
	v_cndmask_b32_e32 v37, v37, v113, vcc
	ds_bpermute_b32 v66, v66, v37
	v_cmp_gt_u32_e64 s[0:1], 2, v118
	s_waitcnt lgkmcnt(0)
	v_add_f32_e32 v66, v37, v66
	v_cndmask_b32_e64 v37, v66, v37, s[0:1]
	v_cmp_lt_i32_e64 s[0:1], v67, v36
	s_nop 1
	v_cndmask_b32_e64 v66, v67, v1, s[0:1]
	v_lshlrev_b32_e32 v66, 2, v66
	ds_bpermute_b32 v66, v66, v37
	v_cmp_gt_u32_e64 s[0:1], 4, v118
	s_waitcnt lgkmcnt(0)
	v_add_f32_e32 v66, v37, v66
	v_cndmask_b32_e64 v37, v66, v37, s[0:1]
	v_add_u32_e32 v66, -8, v1
	v_cmp_lt_i32_e64 s[0:1], v66, v36
	s_nop 1
	v_cndmask_b32_e64 v66, v66, v1, s[0:1]
	v_lshlrev_b32_e32 v66, 2, v66
	ds_bpermute_b32 v66, v66, v37
	v_cmp_gt_u32_e64 s[0:1], 8, v118
	s_waitcnt lgkmcnt(0)
	v_add_f32_e32 v66, v37, v66
	v_cndmask_b32_e64 v37, v66, v37, s[0:1]
	v_add_u32_e32 v66, -16, v1
	v_cmp_lt_i32_e64 s[0:1], v66, v36
	s_nop 1
	v_cndmask_b32_e64 v66, v66, v1, s[0:1]
	v_lshlrev_b32_e32 v66, 2, v66
	ds_bpermute_b32 v66, v66, v37
	v_cmp_gt_u32_e64 s[0:1], 16, v118
	s_waitcnt lgkmcnt(0)
	v_add_f32_e32 v66, v37, v66
	v_cndmask_b32_e64 v37, v66, v37, s[0:1]
	v_subrev_u32_e32 v66, 32, v1
	v_cmp_lt_i32_e64 s[0:1], v66, v36
	s_nop 1
	v_cndmask_b32_e64 v36, v66, v1, s[0:1]
	v_lshlrev_b32_e32 v36, 2, v36
	ds_bpermute_b32 v36, v36, v37
	v_cmp_gt_u32_e64 s[0:1], 32, v118
	v_lshl_add_u32 v66, v118, 2, 0
	v_add_u32_e32 v67, 0x1d000, v66
	v_add_u32_e32 v68, 0x1d200, v66
	s_waitcnt lgkmcnt(0)
	v_add_f32_e32 v36, v37, v36
	v_cndmask_b32_e64 v37, v36, v37, s[0:1]
	ds_bpermute_b32 v36, v106, v37
	ds_write_b32 v67, v37
	v_add_u32_e32 v67, 0x1d100, v66
	s_waitcnt vmcnt(35)
	ds_write_b32 v67, v35
	v_mul_f32_e32 v67, 0x3fb8aa3b, v37
	s_waitcnt lgkmcnt(2)
	v_sub_f32_e32 v37, v36, v37
	v_mul_f32_e32 v37, 0x3fb8aa3b, v37
	v_exp_f32_e32 v67, v67
	v_exp_f32_e32 v37, v37
	v_add_u32_e32 v66, 0x1d300, v66
	ds_write_b32 v68, v67
	ds_write_b32 v66, v37
	s_and_saveexec_b64 s[0:1], vcc
	s_cbranch_execz .LBB0_479
	v_mul_f32_e32 v36, 0x3fb8aa3b, v36
	v_exp_f32_e32 v36, v36
	s_lshl_b64 s[4:5], s[18:19], 2
	s_add_u32 s4, s58, s4
	s_addc_u32 s5, s57, s5
	global_store_dword v34, v36, s[4:5]

; __device__ __forceinline__ float silu_f(float x) { return x * __builtin_amdgcn_rcpf(1.0f + __expf(-x)); }
; __device__ __forceinline__ void gdn_prep_item(LAS unsigned char* lds, int item, int b0, PrepRaw& R, int next_item, const bf16_t* qkv, const float* bg, const float* gconv_w, unsigned char* rec, float* gtarr) {
;     ...
;     __syncthreads();
;     {
;         const int cc = tid & 15, i0 = (tid >> 4) * 2;
;         const float be0 = Bs[i0], be1 = Bs[i0 + 1], eg0 = EG[i0], eg1 = EG[i0 + 1];
; #pragma unroll
;         for (int part = 0; part < 3; ++part) {
;             const int col = part * 1024 + h * 128 + 8 * cc;
;             float y0[8], y1[8];
; #pragma unroll
;             for (int e = 0; e < 8; ++e) { y0[e] = 0.f; y1[e] = 0.f; }
; #pragma unroll
;             for (int j = 0; j < 5; ++j) { const u32x4 v = part < 2 ? R.x[part < 2 ? part : 0][j] : xv[j]; const unsigned vv[4] = {v.x, v.y, v.z, v.w}; float x[8];
; #pragma unroll
;                 for (int e = 0; e < 4; ++e) { x[2 * e] = __uint_as_float(vv[e] << 16); x[2 * e + 1] = __uint_as_float(vv[e] & 0xffff0000u); }
;                 if (j < 4) { const f32x4 wa = *(const f32x4*)(gconv_w + j * CONVCH + col), wb = *(const f32x4*)(gconv_w + j * CONVCH + col + 4);
; #pragma unroll
;                     for (int e = 0; e < 8; ++e) y0[e] += (e < 4 ? wa[e] : wb[e - 4]) * x[e]; }
;                 if (j > 0) { const f32x4 wa = *(const f32x4*)(gconv_w + (j - 1) * CONVCH + col), wb = *(const f32x4*)(gconv_w + (j - 1) * CONVCH + col + 4);
; #pragma unroll
;                     for (int e = 0; e < 8; ++e) y1[e] += (e < 4 ? wa[e] : wb[e - 4]) * x[e]; } }
;             float s0 = 0.f, s1 = 0.f;
; #pragma unroll
;             for (int e = 0; e < 8; ++e) { y0[e] = silu_f(y0[e]); y1[e] = silu_f(y1[e]); s0 += y0[e] * y0[e]; s1 += y1[e] * y1[e]; }
.LBB0_482:
	s_or_b64 exec, exec, s[0:1]
	v_or_b32_e32 v36, s6, v94
	v_lshlrev_b32_e32 v36, 2, v36
	v_mov_b32_e32 v37, v34
	v_lshl_add_u64 v[98:99], s[72:73], 0, v[36:37]
	s_mov_b64 s[0:1], 0x3000
	s_waitcnt lgkmcnt(0)
	s_barrier
	v_lshl_add_u64 v[36:37], v[98:99], 0, s[0:1]
	s_mov_b64 s[0:1], 0x6000
	s_mov_b64 s[0:1], 0x9000
	v_lshl_add_u64 v[36:37], v[98:99], 0, s[0:1]
	s_movk_i32 s0, 0x4000
	v_add_co_u32_e32 v100, vcc, s0, v98
	s_movk_i32 s0, 0x7000
	s_nop 0
	v_addc_co_u32_e32 v101, vcc, 0, v99, vcc
	v_add_co_u32_e32 v102, vcc, s0, v98
	s_mov_b32 s0, 0xa000
	s_nop 0
	v_addc_co_u32_e32 v103, vcc, 0, v99, vcc
	v_add_co_u32_e32 v104, vcc, s0, v98
	v_addc_co_u32_e32 v105, vcc, 0, v99, vcc
	s_waitcnt vmcnt(16)
	v_lshlrev_b32_e32 v132, 16, v4
	v_and_b32_e32 v133, 0xffff0000, v4
	v_lshlrev_b32_e32 v134, 16, v12
	v_and_b32_e32 v135, 0xffff0000, v12
	v_lshlrev_b32_e32 v136, 16, v16
	v_and_b32_e32 v137, 0xffff0000, v16
	v_lshlrev_b32_e32 v138, 16, v20
	v_and_b32_e32 v139, 0xffff0000, v20
	v_lshlrev_b32_e32 v140, 16, v3
	v_and_b32_e32 v141, 0xffff0000, v3
	v_lshlrev_b32_e32 v142, 16, v11
	v_and_b32_e32 v143, 0xffff0000, v11
	v_lshlrev_b32_e32 v144, 16, v15
	v_and_b32_e32 v145, 0xffff0000, v15
	v_lshlrev_b32_e32 v154, 16, v2
	v_and_b32_e32 v155, 0xffff0000, v2
	v_lshlrev_b32_e32 v158, 16, v10
	v_and_b32_e32 v159, 0xffff0000, v10
	v_lshlrev_b32_e32 v160, 16, v14
	v_and_b32_e32 v161, 0xffff0000, v14
	v_lshlrev_b32_e32 v162, 16, v18
	v_and_b32_e32 v163, 0xffff0000, v18
	s_add_i32 s29, s29, 1
	s_add_i32 s0, s99, s96
	s_and_b32 s100, s0, 7
	s_lshr_b32 s101, s0, 3
	s_and_b32 s98, s101, 7
	s_lshr_b32 s101, s101, 3
	s_mul_i32 s98, s98, 33
	s_add_i32 s98, s98, s101
	s_lshl_b32 s98, s98, 3
	s_or_b32 s0, s98, s100
	v_or_b32_e32 v164, 1, v115
	s_cmp_lt_i32 s29, s3
	v_lshlrev_b32_e32 v36, 2, v95
	v_lshlrev_b32_e32 v37, 2, v164
	s_cselect_b32 s14, s0, -1
	s_add_i32 s0, 0, 0x1d100
	s_add_i32 s31, 0, 0x1d200
	v_lshlrev_b32_e32 v124, 16, v5
	v_and_b32_e32 v125, 0xffff0000, v5
	v_add_u32_e32 v96, s0, v36
	v_add_u32_e32 v97, s0, v37
	v_add_u32_e32 v146, s31, v36
	v_add_u32_e32 v147, s31, v37
	ds_read_b32 v36, v96
	ds_read_b32 v37, v97
	ds_read_b32 v96, v146
	ds_read_b32 v97, v147
	v_lshlrev_b32_e32 v126, 16, v13
	v_and_b32_e32 v127, 0xffff0000, v13
	v_lshlrev_b32_e32 v128, 16, v17
	v_and_b32_e32 v129, 0xffff0000, v17
	v_lshlrev_b32_e32 v130, 16, v21
	v_and_b32_e32 v131, 0xffff0000, v21
	v_pk_fma_f32 v[148:149], v[82:83], v[132:133], 0 op_sel_hi:[1,1,0]
	v_pk_fma_f32 v[150:151], v[168:169], v[140:141], 0 op_sel_hi:[1,1,0]
	v_pk_fma_f32 v[156:157], v[166:167], v[154:155], 0 op_sel_hi:[1,1,0]
	v_pk_fma_f32 v[146:147], v[84:85], v[124:125], 0 op_sel_hi:[1,1,0]
	v_pk_fma_f32 v[148:149], v[86:87], v[134:135], v[148:149]
	v_pk_fma_f32 v[148:149], v[90:91], v[136:137], v[148:149]
	v_pk_fma_f32 v[146:147], v[88:89], v[126:127], v[146:147]
	v_pk_fma_f32 v[138:139], v[120:121], v[138:139], v[148:149]
	v_pk_fma_f32 v[146:147], v[92:93], v[128:129], v[146:147]
	v_mul_f32_e32 v148, 0xbfb8aa3b, v138
	v_mul_f32_e32 v149, 0xbfb8aa3b, v139
	v_exp_f32_e32 v148, v148
	v_exp_f32_e32 v149, v149
	v_pk_fma_f32 v[130:131], v[122:123], v[130:131], v[146:147]
	v_add_f32_e32 v148, 1.0, v148
	v_add_f32_e32 v149, 1.0, v149
	v_rcp_f32_e32 v148, v148
	v_rcp_f32_e32 v149, v149
	v_mul_f32_e32 v146, 0xbfb8aa3b, v130
	v_pk_fma_f32 v[150:151], v[72:73], v[142:143], v[150:151]
	v_pk_fma_f32 v[156:157], v[70:71], v[158:159], v[156:157]
	v_pk_fma_f32 v[150:151], v[76:77], v[144:145], v[150:151]
	v_pk_mul_f32 v[138:139], v[138:139], v[148:149]
	v_lshlrev_b32_e32 v148, 16, v19
	v_and_b32_e32 v149, 0xffff0000, v19
	v_pk_fma_f32 v[148:149], v[80:81], v[148:149], v[150:151]
	v_pk_fma_f32 v[156:157], v[74:75], v[160:161], v[156:157]
	v_mul_f32_e32 v150, 0xbfb8aa3b, v148
	v_exp_f32_e32 v152, v150
	v_mul_f32_e32 v150, 0xbfb8aa3b, v149
	v_exp_f32_e32 v153, v150
	v_pk_fma_f32 v[156:157], v[78:79], v[162:163], v[156:157]
	v_add_f32_e32 v152, 1.0, v152
	v_mul_f32_e32 v162, 0xbfb8aa3b, v156
	v_add_f32_e32 v153, 1.0, v153
	v_mul_f32_e32 v163, 0xbfb8aa3b, v157
	v_rcp_f32_e32 v152, v152
	v_rcp_f32_e32 v153, v153
	v_exp_f32_e32 v162, v162
	v_exp_f32_e32 v163, v163
	v_mul_f32_e32 v147, 0xbfb8aa3b, v131
	v_pk_mul_f32 v[148:149], v[148:149], v[152:153]
	v_add_f32_e32 v152, 1.0, v162
	v_add_f32_e32 v153, 1.0, v163
	v_lshlrev_b32_e32 v162, 16, v9
	v_and_b32_e32 v163, 0xffff0000, v9
	v_pk_fma_f32 v[84:85], v[84:85], v[162:163], 0 op_sel_hi:[1,1,0]
	v_exp_f32_e32 v146, v146
	v_pk_fma_f32 v[84:85], v[88:89], v[124:125], v[84:85]
	v_exp_f32_e32 v147, v147
	v_pk_fma_f32 v[84:85], v[92:93], v[126:127], v[84:85]
	v_rcp_f32_e32 v152, v152
	v_pk_fma_f32 v[84:85], v[122:123], v[128:129], v[84:85]
	v_rcp_f32_e32 v153, v153
	v_mul_f32_e32 v88, 0xbfb8aa3b, v84
	v_mul_f32_e32 v89, 0xbfb8aa3b, v85
	v_exp_f32_e32 v88, v88
	v_exp_f32_e32 v89, v89
	v_add_f32_e32 v146, 1.0, v146
	v_add_f32_e32 v147, 1.0, v147
	v_add_f32_e32 v88, 1.0, v88
	v_add_f32_e32 v89, 1.0, v89
	v_rcp_f32_e32 v88, v88
	v_rcp_f32_e32 v89, v89
	v_pk_mul_f32 v[122:123], v[156:157], v[152:153]
	v_rcp_f32_e32 v146, v146
	v_rcp_f32_e32 v147, v147
	v_pk_mul_f32 v[84:85], v[84:85], v[88:89]
	v_lshlrev_b32_e32 v88, 16, v8
	v_and_b32_e32 v89, 0xffff0000, v8
	v_pk_fma_f32 v[82:83], v[82:83], v[88:89], 0 op_sel_hi:[1,1,0]
	v_pk_mul_f32 v[124:125], v[122:123], v[122:123]
	v_pk_fma_f32 v[82:83], v[86:87], v[132:133], v[82:83]
	v_pk_mul_f32 v[92:93], v[148:149], v[148:149]
	v_pk_fma_f32 v[82:83], v[90:91], v[134:135], v[82:83]
	v_lshlrev_b32_e32 v90, 16, v7
	v_and_b32_e32 v91, 0xffff0000, v7
	v_pk_fma_f32 v[68:69], v[168:169], v[90:91], 0 op_sel_hi:[1,1,0]
	v_pk_fma_f32 v[82:83], v[120:121], v[136:137], v[82:83]
; #define LAS __attribute__((address_space(3)))
; __device__ __forceinline__ unsigned cvt_pk_bf16(float lo, float hi) { const bf16x2_t r = __builtin_convertvector((f32x2){lo, hi}, bf16x2_t); return __builtin_bit_cast(unsigned, r); }
; __device__ __forceinline__ float silu_f(float x) { return x * __builtin_amdgcn_rcpf(1.0f + __expf(-x)); }
; __device__ __forceinline__ void gdn_prep_item(LAS unsigned char* lds, int item, int b0, PrepRaw& R, int next_item, const bf16_t* qkv, const float* bg, const float* gconv_w, unsigned char* rec, float* gtarr) {
;     ...
;             float s0 = 0.f, s1 = 0.f;
; #pragma unroll
;             for (int e = 0; e < 8; ++e) { y0[e] = silu_f(y0[e]); y1[e] = silu_f(y1[e]); s0 += y0[e] * y0[e]; s1 += y1[e] * y1[e]; }
;             if (part < 2) {
;                 s0 = row16_sum(s0); s1 = row16_sum(s1);
;                 float sc0 = rsqrtf(s0 + EPS), sc1 = rsqrtf(s1 + EPS); if (part == 0) { sc0 *= 0.08838834764831845f; sc1 *= 0.08838834764831845f; }
; #pragma unroll
;                 for (int e = 0; e < 8; ++e) { y0[e] *= sc0; y1[e] *= sc1; }
;                 LAS unsigned char* img = lds + (part == 0 ? P2_QN : P2_KN);
;                 u32x4 w0, w1; w0.x = cvt_pk_bf16(y0[0], y0[1]); w0.y = cvt_pk_bf16(y0[2], y0[3]); w0.z = cvt_pk_bf16(y0[4], y0[5]); w0.w = cvt_pk_bf16(y0[6], y0[7]);
;                 w1.x = cvt_pk_bf16(y1[0], y1[1]); w1.y = cvt_pk_bf16(y1[2], y1[3]); w1.z = cvt_pk_bf16(y1[4], y1[5]); w1.w = cvt_pk_bf16(y1[6], y1[7]);
;                 *(LAS u32x4*)(img + (i0 * 136 + 8 * cc) * 2) = w0; *(LAS u32x4*)(img + ((i0 + 1) * 136 + 8 * cc) * 2) = w1;
	v_pk_fma_f32 v[68:69], v[72:73], v[140:141], v[68:69]
	v_mul_f32_e32 v86, 0xbfb8aa3b, v82
	v_pk_fma_f32 v[68:69], v[76:77], v[142:143], v[68:69]
	v_exp_f32_e32 v88, v86
	v_pk_fma_f32 v[68:69], v[80:81], v[144:145], v[68:69]
	v_lshlrev_b32_e32 v80, 16, v6
	v_and_b32_e32 v81, 0xffff0000, v6
	v_pk_fma_f32 v[66:67], v[166:167], v[80:81], 0 op_sel_hi:[1,1,0]
	v_mul_f32_e32 v72, 0xbfb8aa3b, v68
	v_pk_fma_f32 v[66:67], v[70:71], v[154:155], v[66:67]
	v_exp_f32_e32 v76, v72
	v_pk_fma_f32 v[66:67], v[74:75], v[158:159], v[66:67]
	v_mul_f32_e32 v72, 0xbfb8aa3b, v69
	v_pk_fma_f32 v[66:67], v[78:79], v[160:161], v[66:67]
	v_exp_f32_e32 v77, v72
	v_mul_f32_e32 v70, 0xbfb8aa3b, v66
	v_mul_f32_e32 v71, 0xbfb8aa3b, v67
	v_exp_f32_e32 v70, v70
	v_exp_f32_e32 v71, v71
	v_mul_f32_e32 v86, 0xbfb8aa3b, v83
	v_exp_f32_e32 v89, v86
	v_add_f32_e32 v70, 1.0, v70
	v_add_f32_e32 v71, 1.0, v71
	v_add_f32_e32 v76, 1.0, v76
	v_add_f32_e32 v77, 1.0, v77
	v_rcp_f32_e32 v70, v70
	v_rcp_f32_e32 v71, v71
	v_rcp_f32_e32 v76, v76
	v_rcp_f32_e32 v77, v77
	v_add_f32_e32 v88, 1.0, v88
	v_add_f32_e32 v89, 1.0, v89
	v_rcp_f32_e32 v88, v88
	v_rcp_f32_e32 v89, v89
	v_pk_mul_f32 v[66:67], v[66:67], v[70:71]
	v_pk_mul_f32 v[68:69], v[68:69], v[76:77]
	v_pk_mul_f32 v[70:71], v[66:67], v[66:67]
	v_pk_mul_f32 v[76:77], v[68:69], v[68:69]
	v_mov_b32_e32 v78, v124
	v_mov_b32_e32 v79, v70
	v_mov_b32_e32 v70, v125
	v_pk_mul_f32 v[72:73], v[82:83], v[88:89]
	v_pk_add_f32 v[70:71], v[78:79], v[70:71]
	v_mov_b32_e32 v78, v92
	v_mov_b32_e32 v79, v76
	v_pk_mul_f32 v[150:151], v[138:139], v[138:139]
	v_pk_mul_f32 v[74:75], v[72:73], v[72:73]
	v_pk_add_f32 v[70:71], v[78:79], v[70:71]
	v_mov_b32_e32 v76, v93
	v_pk_mul_f32 v[130:131], v[130:131], v[146:147]
	v_pk_add_f32 v[70:71], v[76:77], v[70:71]
	v_mov_b32_e32 v76, v150
	v_mov_b32_e32 v77, v74
	v_pk_mul_f32 v[146:147], v[130:131], v[130:131]
	v_pk_mul_f32 v[86:87], v[84:85], v[84:85]
	v_pk_add_f32 v[70:71], v[76:77], v[70:71]
	v_mov_b32_e32 v74, v151
	v_pk_add_f32 v[70:71], v[74:75], v[70:71]
	v_mov_b32_e32 v74, v146
	v_mov_b32_e32 v75, v86
	v_pk_add_f32 v[70:71], v[74:75], v[70:71]
	v_mov_b32_e32 v86, v147
	v_pk_add_f32 v[70:71], v[86:87], v[70:71]
	v_mov_b32_e32 v74, v34
	v_mov_b32_e32 v75, v34
	v_mad_u64_u32 v[76:77], s[0:1], v164, s23, v[94:95]
	v_mov_b32_dpp v74, v70 quad_perm:[1,0,3,2] row_mask:0xf bank_mask:0xf
	v_mov_b32_dpp v75, v71 quad_perm:[1,0,3,2] row_mask:0xf bank_mask:0xf
	v_pk_add_f32 v[70:71], v[70:71], v[74:75]
	v_mov_b32_e32 v74, v34
	v_mov_b32_e32 v75, v34
	v_lshl_add_u32 v160, v76, 1, 0
	v_mov_b32_dpp v74, v70 quad_perm:[2,3,0,1] row_mask:0xf bank_mask:0xf
	v_mov_b32_dpp v75, v71 quad_perm:[2,3,0,1] row_mask:0xf bank_mask:0xf
	v_pk_add_f32 v[70:71], v[70:71], v[74:75]
	v_mov_b32_e32 v74, v34
	v_mov_b32_e32 v75, v34
	s_nop 0
	v_mov_b32_dpp v74, v70 row_ror:4 row_mask:0xf bank_mask:0xf
	v_mov_b32_dpp v75, v71 row_ror:4 row_mask:0xf bank_mask:0xf
	v_pk_add_f32 v[70:71], v[70:71], v[74:75]
	v_mov_b32_e32 v74, v34
	v_mov_b32_e32 v75, v34
	s_nop 0
	v_mov_b32_dpp v74, v70 row_ror:8 row_mask:0xf bank_mask:0xf
	v_mov_b32_dpp v75, v71 row_ror:8 row_mask:0xf bank_mask:0xf
	v_pk_add_f32 v[70:71], v[70:71], v[74:75]
	s_nop 0
	v_pk_add_f32 v[70:71], v[70:71], s[16:17] op_sel_hi:[1,0]
	s_nop 0
	v_mul_f32_e32 v74, 0x4b800000, v70
	v_cmp_gt_f32_e32 vcc, s24, v70
	s_nop 1
	v_cndmask_b32_e32 v70, v70, v74, vcc
	v_rsq_f32_e32 v70, v70
	v_mad_u64_u32 v[74:75], s[0:1], v95, s23, v[94:95]
	v_lshl_add_u32 v94, v74, 1, 0
	v_mul_f32_e32 v75, 0x45800000, v70
	v_cndmask_b32_e32 v70, v70, v75, vcc
	v_mul_f32_e32 v70, 0x3db504f3, v70
	v_mul_f32_e32 v75, 0x4b800000, v71
	v_cmp_gt_f32_e32 vcc, s24, v71
	v_pk_mul_f32 v[78:79], v[122:123], v[70:71] op_sel_hi:[1,0]
	s_nop 0
	v_cndmask_b32_e32 v71, v71, v75, vcc
	v_rsq_f32_e32 v71, v71
	s_nop 0
	v_pk_mul_f32 v[80:81], v[148:149], v[70:71] op_sel_hi:[1,0]
	v_pk_mul_f32 v[82:83], v[138:139], v[70:71] op_sel_hi:[1,0]
	v_pk_mul_f32 v[86:87], v[130:131], v[70:71] op_sel_hi:[1,0]
	v_mul_f32_e32 v70, 0x45800000, v71
	v_cndmask_b32_e32 v70, v71, v70, vcc
	v_mul_f32_e32 v70, 0x3db504f3, v70
	v_pk_mul_f32 v[66:67], v[66:67], v[70:71] op_sel_hi:[1,0]
	v_pk_mul_f32 v[68:69], v[68:69], v[70:71] op_sel_hi:[1,0]
	v_pk_mul_f32 v[72:73], v[72:73], v[70:71] op_sel_hi:[1,0]
	v_pk_mul_f32 v[70:71], v[84:85], v[70:71] op_sel_hi:[1,0]
	v_cvt_pk_bf16_f32 v66, v66, v67
	v_cvt_pk_bf16_f32 v67, v68, v69
	v_cvt_pk_bf16_f32 v68, v72, v73
	v_cvt_pk_bf16_f32 v69, v70, v71
	v_cvt_pk_bf16_f32 v70, v78, v79
	v_cvt_pk_bf16_f32 v71, v80, v81
	v_cvt_pk_bf16_f32 v72, v82, v83
	v_cvt_pk_bf16_f32 v73, v86, v87
	ds_write_b128 v94, v[66:69]
	ds_write_b128 v160, v[70:73]
	s_mov_b64 s[0:1], 0x1000
	v_lshl_add_u64 v[66:67], v[98:99], 0, s[0:1]
	s_movk_i32 s0, 0x2000
	v_add_co_u32_e32 v82, vcc, s0, v98
	s_mov_b64 s[0:1], 0x4000
	s_nop 0
	v_addc_co_u32_e32 v83, vcc, 0, v99, vcc
	v_lshl_add_u64 v[70:71], v[98:99], 0, s[0:1]
	s_mov_b64 s[0:1], 0x7000
	s_nop 0
	v_lshl_add_u64 v[74:75], v[98:99], 0, s[0:1]
	s_mov_b64 s[0:1], 0xa000
	s_nop 0
	v_lshl_add_u64 v[78:79], v[98:99], 0, s[0:1]
	s_nop 0
	v_lshlrev_b32_e32 v136, 16, v27
	v_and_b32_e32 v137, 0xffff0000, v27
	v_lshlrev_b32_e32 v138, 16, v31
	v_and_b32_e32 v139, 0xffff0000, v31
	v_lshlrev_b32_e32 v140, 16, v39
	v_and_b32_e32 v141, 0xffff0000, v39
	v_lshlrev_b32_e32 v142, 16, v43
	v_and_b32_e32 v143, 0xffff0000, v43
	v_lshlrev_b32_e32 v144, 16, v26
	v_and_b32_e32 v145, 0xffff0000, v26
	v_lshlrev_b32_e32 v146, 16, v30
	v_and_b32_e32 v147, 0xffff0000, v30
	v_lshlrev_b32_e32 v148, 16, v38
	v_and_b32_e32 v149, 0xffff0000, v38
	v_lshlrev_b32_e32 v150, 16, v42
	v_and_b32_e32 v151, 0xffff0000, v42
	v_lshlrev_b32_e32 v92, 16, v29
	v_and_b32_e32 v93, 0xffff0000, v29
	v_lshlrev_b32_e32 v104, 16, v33
	v_and_b32_e32 v105, 0xffff0000, v33
	v_lshlrev_b32_e32 v124, 16, v41
	v_and_b32_e32 v125, 0xffff0000, v41
	v_lshlrev_b32_e32 v128, 16, v28
	v_and_b32_e32 v129, 0xffff0000, v28
	v_lshlrev_b32_e32 v130, 16, v32
	v_and_b32_e32 v131, 0xffff0000, v32
	v_lshlrev_b32_e32 v132, 16, v40
	v_and_b32_e32 v133, 0xffff0000, v40
	v_lshlrev_b32_e32 v134, 16, v44
	v_and_b32_e32 v135, 0xffff0000, v44
	v_lshlrev_b32_e32 v126, 16, v45
	v_and_b32_e32 v127, 0xffff0000, v45
	s_movk_i32 s0, 0x240
	s_waitcnt vmcnt(8)
; __device__ __forceinline__ float silu_f(float x) { return x * __builtin_amdgcn_rcpf(1.0f + __expf(-x)); }
; __device__ __forceinline__ void gdn_prep_item(LAS unsigned char* lds, int item, int b0, PrepRaw& R, int next_item, const bf16_t* qkv, const float* bg, const float* gconv_w, unsigned char* rec, float* gtarr) {
;     ...
;             for (int j = 0; j < 5; ++j) { const u32x4 v = part < 2 ? R.x[part < 2 ? part : 0][j] : xv[j]; const unsigned vv[4] = {v.x, v.y, v.z, v.w}; float x[8];
; #pragma unroll
;                 for (int e = 0; e < 4; ++e) { x[2 * e] = __uint_as_float(vv[e] << 16); x[2 * e + 1] = __uint_as_float(vv[e] & 0xffff0000u); }
;                 if (j < 4) { const f32x4 wa = *(const f32x4*)(gconv_w + j * CONVCH + col), wb = *(const f32x4*)(gconv_w + j * CONVCH + col + 4);
; #pragma unroll
;                     for (int e = 0; e < 8; ++e) y0[e] += (e < 4 ? wa[e] : wb[e - 4]) * x[e]; }
;                 if (j > 0) { const f32x4 wa = *(const f32x4*)(gconv_w + (j - 1) * CONVCH + col), wb = *(const f32x4*)(gconv_w + (j - 1) * CONVCH + col + 4);
; #pragma unroll
;                     for (int e = 0; e < 8; ++e) y1[e] += (e < 4 ? wa[e] : wb[e - 4]) * x[e]; } }
;             float s0 = 0.f, s1 = 0.f;
; #pragma unroll
;             for (int e = 0; e < 8; ++e) { y0[e] = silu_f(y0[e]); y1[e] = silu_f(y1[e]); s0 += y0[e] * y0[e]; s1 += y1[e] * y1[e]; }
;             if (part < 2) {
;                 s0 = row16_sum(s0); s1 = row16_sum(s1);
;                 float sc0 = rsqrtf(s0 + EPS), sc1 = rsqrtf(s1 + EPS); if (part == 0) { sc0 *= 0.08838834764831845f; sc1 *= 0.08838834764831845f; }
	v_pk_fma_f32 v[152:153], v[172:173], v[92:93], 0 op_sel_hi:[1,1,0]
	v_pk_fma_f32 v[154:155], v[170:171], v[128:129], 0 op_sel_hi:[1,1,0]
	v_pk_fma_f32 v[156:157], v[176:177], v[136:137], 0 op_sel_hi:[1,1,0]
	v_pk_fma_f32 v[158:159], v[174:175], v[144:145], 0 op_sel_hi:[1,1,0]
	v_pk_fma_f32 v[156:157], v[184:185], v[138:139], v[156:157]
	v_pk_fma_f32 v[158:159], v[182:183], v[146:147], v[158:159]
	v_pk_fma_f32 v[152:153], v[180:181], v[104:105], v[152:153]
	v_pk_fma_f32 v[156:157], v[192:193], v[140:141], v[156:157]
	v_pk_fma_f32 v[158:159], v[190:191], v[148:149], v[158:159]
	v_pk_fma_f32 v[142:143], v[200:201], v[142:143], v[156:157]
	v_pk_fma_f32 v[150:151], v[198:199], v[150:151], v[158:159]
	v_mul_f32_e32 v156, 0xbfb8aa3b, v142
	v_mul_f32_e32 v157, 0xbfb8aa3b, v143
	v_exp_f32_e32 v156, v156
	v_exp_f32_e32 v157, v157
	v_mul_f32_e32 v158, 0xbfb8aa3b, v150
	v_mul_f32_e32 v159, 0xbfb8aa3b, v151
	v_add_f32_e32 v156, 1.0, v156
	v_add_f32_e32 v157, 1.0, v157
	v_exp_f32_e32 v158, v158
	v_rcp_f32_e32 v156, v156
	v_rcp_f32_e32 v157, v157
	v_exp_f32_e32 v159, v159
	v_pk_fma_f32 v[154:155], v[178:179], v[130:131], v[154:155]
	v_pk_fma_f32 v[152:153], v[188:189], v[124:125], v[152:153]
	v_pk_mul_f32 v[142:143], v[142:143], v[156:157]
	v_add_f32_e32 v156, 1.0, v158
	v_add_f32_e32 v157, 1.0, v159
	v_lshlrev_b32_e32 v158, 16, v25
	v_and_b32_e32 v159, 0xffff0000, v25
	v_pk_fma_f32 v[86:87], v[172:173], v[158:159], 0 op_sel_hi:[1,1,0]
	v_pk_fma_f32 v[154:155], v[186:187], v[132:133], v[154:155]
	v_pk_fma_f32 v[86:87], v[180:181], v[92:93], v[86:87]
	v_pk_fma_f32 v[134:135], v[194:195], v[134:135], v[154:155]
	v_pk_fma_f32 v[86:87], v[188:189], v[104:105], v[86:87]
	v_mul_f32_e32 v154, 0xbfb8aa3b, v134
	v_pk_fma_f32 v[86:87], v[196:197], v[124:125], v[86:87]
	v_mul_f32_e32 v155, 0xbfb8aa3b, v135
	v_mul_f32_e32 v90, 0xbfb8aa3b, v86
	v_mul_f32_e32 v91, 0xbfb8aa3b, v87
	v_exp_f32_e32 v90, v90
	v_exp_f32_e32 v91, v91
	v_pk_fma_f32 v[126:127], v[196:197], v[126:127], v[152:153]
	v_exp_f32_e32 v154, v154
	v_add_f32_e32 v90, 1.0, v90
	v_add_f32_e32 v91, 1.0, v91
	v_rcp_f32_e32 v90, v90
	v_rcp_f32_e32 v91, v91
	v_exp_f32_e32 v155, v155
	v_mul_f32_e32 v152, 0xbfb8aa3b, v126
	v_mul_f32_e32 v153, 0xbfb8aa3b, v127
	v_pk_mul_f32 v[86:87], v[86:87], v[90:91]
	v_lshlrev_b32_e32 v90, 16, v24
	v_and_b32_e32 v91, 0xffff0000, v24
	v_pk_fma_f32 v[84:85], v[170:171], v[90:91], 0 op_sel_hi:[1,1,0]
	v_exp_f32_e32 v152, v152
	v_pk_fma_f32 v[84:85], v[178:179], v[128:129], v[84:85]
	v_exp_f32_e32 v153, v153
	v_pk_fma_f32 v[84:85], v[186:187], v[130:131], v[84:85]
	v_rcp_f32_e32 v156, v156
	v_pk_fma_f32 v[84:85], v[194:195], v[132:133], v[84:85]
	v_lshlrev_b32_e32 v100, 16, v23
	v_and_b32_e32 v101, 0xffff0000, v23
	v_pk_fma_f32 v[68:69], v[176:177], v[100:101], 0 op_sel_hi:[1,1,0]
	v_mul_f32_e32 v88, 0xbfb8aa3b, v84
	v_pk_fma_f32 v[68:69], v[184:185], v[136:137], v[68:69]
	v_exp_f32_e32 v90, v88
	v_pk_fma_f32 v[68:69], v[192:193], v[138:139], v[68:69]
	v_mul_f32_e32 v88, 0xbfb8aa3b, v85
	v_pk_fma_f32 v[68:69], v[200:201], v[140:141], v[68:69]
	v_lshlrev_b32_e32 v80, 16, v22
	v_and_b32_e32 v81, 0xffff0000, v22
	v_pk_fma_f32 v[66:67], v[174:175], v[80:81], 0 op_sel_hi:[1,1,0]
	v_mul_f32_e32 v72, 0xbfb8aa3b, v68
	v_pk_fma_f32 v[66:67], v[182:183], v[144:145], v[66:67]
	v_exp_f32_e32 v76, v72
	v_pk_fma_f32 v[66:67], v[190:191], v[146:147], v[66:67]
	v_mul_f32_e32 v72, 0xbfb8aa3b, v69
	v_pk_fma_f32 v[66:67], v[198:199], v[148:149], v[66:67]
	v_exp_f32_e32 v77, v72
	v_mul_f32_e32 v70, 0xbfb8aa3b, v66
	v_mul_f32_e32 v71, 0xbfb8aa3b, v67
	v_exp_f32_e32 v70, v70
	v_exp_f32_e32 v71, v71
	v_exp_f32_e32 v91, v88
	v_rcp_f32_e32 v157, v157
	v_add_f32_e32 v70, 1.0, v70
	v_add_f32_e32 v71, 1.0, v71
	v_add_f32_e32 v76, 1.0, v76
	v_add_f32_e32 v77, 1.0, v77
	v_rcp_f32_e32 v70, v70
	v_rcp_f32_e32 v71, v71
	v_rcp_f32_e32 v76, v76
	v_rcp_f32_e32 v77, v77
	v_add_f32_e32 v154, 1.0, v154
	v_add_f32_e32 v155, 1.0, v155
	v_add_f32_e32 v90, 1.0, v90
	v_add_f32_e32 v91, 1.0, v91
	v_rcp_f32_e32 v154, v154
	v_rcp_f32_e32 v155, v155
	v_rcp_f32_e32 v90, v90
	v_rcp_f32_e32 v91, v91
	v_add_f32_e32 v152, 1.0, v152
	v_add_f32_e32 v153, 1.0, v153
	v_pk_mul_f32 v[102:103], v[150:151], v[156:157]
	v_pk_mul_f32 v[66:67], v[66:67], v[70:71]
	v_rcp_f32_e32 v152, v152
	v_rcp_f32_e32 v153, v153
	v_pk_mul_f32 v[104:105], v[102:103], v[102:103]
	v_pk_mul_f32 v[68:69], v[68:69], v[76:77]
	v_pk_mul_f32 v[70:71], v[66:67], v[66:67]
	v_pk_mul_f32 v[92:93], v[142:143], v[142:143]
	v_pk_mul_f32 v[76:77], v[68:69], v[68:69]
	v_mov_b32_e32 v78, v104
	v_mov_b32_e32 v79, v70
	v_mov_b32_e32 v70, v105
	v_pk_mul_f32 v[134:135], v[134:135], v[154:155]
	v_pk_mul_f32 v[72:73], v[84:85], v[90:91]
	v_pk_add_f32 v[70:71], v[78:79], v[70:71]
	v_mov_b32_e32 v78, v92
	v_mov_b32_e32 v79, v76
	v_pk_mul_f32 v[154:155], v[134:135], v[134:135]
	v_pk_mul_f32 v[74:75], v[72:73], v[72:73]
	v_pk_add_f32 v[70:71], v[78:79], v[70:71]
	v_mov_b32_e32 v76, v93
	v_pk_mul_f32 v[126:127], v[126:127], v[152:153]
	v_pk_add_f32 v[70:71], v[76:77], v[70:71]
	v_mov_b32_e32 v76, v154
	v_mov_b32_e32 v77, v74
	v_pk_mul_f32 v[152:153], v[126:127], v[126:127]
	v_pk_mul_f32 v[88:89], v[86:87], v[86:87]
	v_pk_add_f32 v[70:71], v[76:77], v[70:71]
	v_mov_b32_e32 v74, v155
	v_pk_add_f32 v[70:71], v[74:75], v[70:71]
	v_mov_b32_e32 v74, v152
	v_mov_b32_e32 v75, v88
	v_pk_add_f32 v[70:71], v[74:75], v[70:71]
	v_mov_b32_e32 v88, v153
	v_pk_add_f32 v[70:71], v[88:89], v[70:71]
	v_mov_b32_e32 v74, v34
	v_mov_b32_e32 v75, v34
	s_nop 0
	v_mov_b32_dpp v74, v70 quad_perm:[1,0,3,2] row_mask:0xf bank_mask:0xf
	v_mov_b32_dpp v75, v71 quad_perm:[1,0,3,2] row_mask:0xf bank_mask:0xf
; #define LAS __attribute__((address_space(3)))
; __device__ __forceinline__ unsigned cvt_pk_bf16(float lo, float hi) { const bf16x2_t r = __builtin_convertvector((f32x2){lo, hi}, bf16x2_t); return __builtin_bit_cast(unsigned, r); }
; __device__ __forceinline__ void gdn_prep_item(LAS unsigned char* lds, int item, int b0, PrepRaw& R, int next_item, const bf16_t* qkv, const float* bg, const float* gconv_w, unsigned char* rec, float* gtarr) {
;     ...
;                 LAS unsigned char* img = lds + (part == 0 ? P2_QN : P2_KN);
;                 u32x4 w0, w1; w0.x = cvt_pk_bf16(y0[0], y0[1]); w0.y = cvt_pk_bf16(y0[2], y0[3]); w0.z = cvt_pk_bf16(y0[4], y0[5]); w0.w = cvt_pk_bf16(y0[6], y0[7]);
;                 w1.x = cvt_pk_bf16(y1[0], y1[1]); w1.y = cvt_pk_bf16(y1[2], y1[3]); w1.z = cvt_pk_bf16(y1[4], y1[5]); w1.w = cvt_pk_bf16(y1[6], y1[7]);
;                 *(LAS u32x4*)(img + (i0 * 136 + 8 * cc) * 2) = w0; *(LAS u32x4*)(img + ((i0 + 1) * 136 + 8 * cc) * 2) = w1;
;                 if (part == 1) {
;                     const float f0 = be0 * eg0, f1 = be1 * eg1;
; #pragma unroll
;                     for (int e = 0; e < 8; ++e) *(LAS unsigned*)(lds + P2_KBT + ((8 * cc + e) * 72 + i0) * 2) = cvt_pk_bf16(y0[e] * f0, y1[e] * f1);
;                 }
;             } else {
; #pragma unroll
;                 for (int e = 0; e < 8; ++e) *(LAS unsigned*)(lds + P2_VBT + ((8 * cc + e) * 72 + i0) * 2) = cvt_pk_bf16(y0[e] * be0, y1[e] * be1);
	v_pk_add_f32 v[70:71], v[70:71], v[74:75]
	v_mov_b32_e32 v74, v34
	v_mov_b32_e32 v75, v34
	s_nop 0
	v_mov_b32_dpp v74, v70 quad_perm:[2,3,0,1] row_mask:0xf bank_mask:0xf
	v_mov_b32_dpp v75, v71 quad_perm:[2,3,0,1] row_mask:0xf bank_mask:0xf
	v_pk_add_f32 v[70:71], v[70:71], v[74:75]
	v_mov_b32_e32 v74, v34
	v_mov_b32_e32 v75, v34
	s_nop 0
	v_mov_b32_dpp v74, v70 row_ror:4 row_mask:0xf bank_mask:0xf
	v_mov_b32_dpp v75, v71 row_ror:4 row_mask:0xf bank_mask:0xf
	v_pk_add_f32 v[70:71], v[70:71], v[74:75]
	v_mov_b32_e32 v74, v34
	v_mov_b32_e32 v75, v34
	s_nop 0
	v_mov_b32_dpp v74, v70 row_ror:8 row_mask:0xf bank_mask:0xf
	v_mov_b32_dpp v75, v71 row_ror:8 row_mask:0xf bank_mask:0xf
	v_pk_add_f32 v[70:71], v[70:71], v[74:75]
	s_nop 0
	v_pk_add_f32 v[70:71], v[70:71], s[16:17] op_sel_hi:[1,0]
	s_nop 0
	v_mul_f32_e32 v74, 0x4b800000, v70
	v_cmp_gt_f32_e32 vcc, s24, v70
	v_mul_f32_e32 v76, 0x4b800000, v71
	s_nop 0
	v_cndmask_b32_e32 v70, v70, v74, vcc
	v_rsq_f32_e32 v70, v70
	s_nop 0
	v_mul_f32_e32 v74, 0x45800000, v70
	v_cndmask_b32_e32 v70, v70, v74, vcc
	v_cmp_gt_f32_e32 vcc, s24, v71
	v_pk_mul_f32 v[74:75], v[102:103], v[70:71] op_sel_hi:[1,0]
	s_nop 0
	v_cndmask_b32_e32 v71, v71, v76, vcc
	v_rsq_f32_e32 v71, v71
	s_nop 0
	v_pk_mul_f32 v[76:77], v[142:143], v[70:71] op_sel_hi:[1,0]
	v_pk_mul_f32 v[78:79], v[134:135], v[70:71] op_sel_hi:[1,0]
	v_pk_mul_f32 v[80:81], v[126:127], v[70:71] op_sel_hi:[1,0]
	v_mul_f32_e32 v70, 0x45800000, v71
	v_cndmask_b32_e32 v70, v71, v70, vcc
	v_pk_mul_f32 v[84:85], v[66:67], v[70:71] op_sel_hi:[1,0]
	v_pk_mul_f32 v[88:89], v[68:69], v[70:71] op_sel_hi:[1,0]
	v_pk_mul_f32 v[90:91], v[72:73], v[70:71] op_sel_hi:[1,0]
	v_pk_mul_f32 v[86:87], v[86:87], v[70:71] op_sel_hi:[1,0]
	v_cvt_pk_bf16_f32 v66, v84, v85
	v_cvt_pk_bf16_f32 v67, v88, v89
	v_cvt_pk_bf16_f32 v68, v90, v91
	v_cvt_pk_bf16_f32 v69, v86, v87
	v_cvt_pk_bf16_f32 v70, v74, v75
	v_cvt_pk_bf16_f32 v71, v76, v77
	v_cvt_pk_bf16_f32 v72, v78, v79
	v_cvt_pk_bf16_f32 v73, v80, v81
	ds_write_b128 v94, v[66:69] offset:17408
	ds_write_b128 v160, v[70:73] offset:17408
	s_waitcnt lgkmcnt(4)
	v_pk_mul_f32 v[66:67], v[36:37], v[96:97]
	v_mov_b32_e32 v68, v84
	v_mov_b32_e32 v69, v74
	v_pk_mul_f32 v[68:69], v[66:67], v[68:69]
	v_mov_b32_e32 v74, v85
	v_cvt_pk_bf16_f32 v70, v68, v69
	v_mad_u32_u24 v68, v114, s0, v95
	v_lshl_add_u32 v84, v68, 1, 0
	v_pk_mul_f32 v[68:69], v[66:67], v[74:75]
	v_add_u32_e32 v71, 0xd000, v84
	v_cvt_pk_bf16_f32 v68, v68, v69
	ds_write2_b32 v71, v70, v68 offset1:36
	v_mov_b32_e32 v68, v88
	v_mov_b32_e32 v69, v76
	v_pk_mul_f32 v[68:69], v[66:67], v[68:69]
	v_mov_b32_e32 v76, v89
	v_cvt_pk_bf16_f32 v70, v68, v69
	v_pk_mul_f32 v[68:69], v[66:67], v[76:77]
	s_nop 0
	v_cvt_pk_bf16_f32 v68, v68, v69
	ds_write2_b32 v71, v70, v68 offset0:72 offset1:108
	v_mov_b32_e32 v68, v90
	v_mov_b32_e32 v69, v78
	v_pk_mul_f32 v[68:69], v[66:67], v[68:69]
	v_mov_b32_e32 v78, v91
	v_cvt_pk_bf16_f32 v70, v68, v69
	v_pk_mul_f32 v[68:69], v[66:67], v[78:79]
	s_nop 0
	v_cvt_pk_bf16_f32 v68, v68, v69
	ds_write2_b32 v71, v70, v68 offset0:144 offset1:180
	v_mov_b32_e32 v68, v86
	v_mov_b32_e32 v69, v80
	v_mov_b32_e32 v80, v87
	v_pk_mul_f32 v[68:69], v[66:67], v[68:69]
	v_pk_mul_f32 v[66:67], v[66:67], v[80:81]
	v_cvt_pk_bf16_f32 v68, v68, v69
	v_cvt_pk_bf16_f32 v66, v66, v67
	ds_write2_b32 v71, v68, v66 offset0:216 offset1:252
	s_waitcnt vmcnt(0)
	s_movk_i32 s0, 0x5000
	v_add_co_u32_e32 v66, vcc, s0, v98
	s_mov_b32 s0, 0x8000
	s_nop 0
	v_addc_co_u32_e32 v67, vcc, 0, v99, vcc
	v_add_co_u32_e32 v70, vcc, s0, v98
	s_nop 0
	v_addc_co_u32_e32 v71, vcc, 0, v99, vcc
	s_mov_b32 s0, 0xb000
	v_add_co_u32_e32 v74, vcc, s0, v98
	s_nop 0
	v_addc_co_u32_e32 v75, vcc, 0, v99, vcc
	s_mov_b64 s[0:1], 0x2000
	s_mov_b64 s[4:5], 0x5000
	v_lshlrev_b32_e32 v101, 16, v54
	v_lshlrev_b32_e32 v105, 16, v62
	v_and_b32_e32 v123, 0xffff0000, v54
	v_and_b32_e32 v127, 0xffff0000, v62
	v_lshlrev_b32_e32 v130, 16, v47
	v_lshlrev_b32_e32 v133, 16, v51
	v_lshlrev_b32_e32 v135, 16, v63
	v_and_b32_e32 v54, 0xffff0000, v47
	v_and_b32_e32 v47, 0xffff0000, v51
	v_and_b32_e32 v51, 0xffff0000, v63
	v_lshl_add_u64 v[62:63], v[98:99], 0, s[0:1]
	v_lshl_add_u64 v[78:79], v[98:99], 0, s[4:5]
	s_mov_b64 s[6:7], 0x8000
	v_add_u32_e32 v138, 0x8800, v84
	s_mov_b64 s[8:9], 0xb000
	v_lshl_add_u64 v[80:81], v[98:99], 0, s[6:7]
	v_lshl_add_u64 v[98:99], v[98:99], 0, s[8:9]
	s_nop 0
	v_lshlrev_b32_e32 v100, 16, v46
	v_and_b32_e32 v122, 0xffff0000, v46
	v_lshlrev_b32_e32 v103, 16, v50
	v_and_b32_e32 v125, 0xffff0000, v50
	v_lshlrev_b32_e32 v131, 16, v55
	v_mov_b32_e32 v102, v101
	v_mov_b32_e32 v124, v123
	v_mov_b32_e32 v104, v103
	v_mov_b32_e32 v126, v125
	v_mov_b32_e32 v132, v131
	v_lshlrev_b32_e32 v121, 16, v58
	v_and_b32_e32 v129, 0xffff0000, v58
	v_mov_b32_e32 v120, v105
	v_mov_b32_e32 v128, v127
	v_mov_b32_e32 v134, v133
	v_lshlrev_b32_e32 v137, 16, v59
	v_and_b32_e32 v55, 0xffff0000, v55
	v_mov_b32_e32 v136, v135
	v_mov_b32_e32 v46, v55
	v_mov_b32_e32 v50, v47
	v_pk_fma_f32 v[62:63], v[202:203], v[100:101], 0 op_sel_hi:[0,1,0]
	v_pk_fma_f32 v[94:95], v[202:203], v[122:123], 0 op_sel:[1,0,0] op_sel_hi:[1,1,0]
	v_pk_fma_f32 v[98:99], v[204:205], v[130:131], 0 op_sel_hi:[0,1,0]
	v_mov_b32_e32 v58, v205
	v_pk_fma_f32 v[62:63], v[206:207], v[102:103], v[62:63] op_sel_hi:[0,1,1]
	v_pk_fma_f32 v[66:67], v[206:207], v[124:125], v[94:95] op_sel:[1,0,0]
	v_pk_fma_f32 v[94:95], v[208:209], v[132:133], v[98:99] op_sel_hi:[0,1,1]
	v_pk_fma_f32 v[62:63], v[210:211], v[104:105], v[62:63] op_sel_hi:[0,1,1]
	v_pk_fma_f32 v[66:67], v[210:211], v[126:127], v[66:67] op_sel:[1,0,0]
	v_pk_fma_f32 v[70:71], v[212:213], v[134:135], v[94:95] op_sel_hi:[0,1,1]
; __device__ __forceinline__ void gdn_prep_item(LAS unsigned char* lds, int item, int b0, PrepRaw& R, int next_item, const bf16_t* qkv, const float* bg, const float* gconv_w, unsigned char* rec, float* gtarr) {
;     ...
;             for (int j = 0; j < 5; ++j) { const u32x4 v = part < 2 ? R.x[part < 2 ? part : 0][j] : xv[j]; const unsigned vv[4] = {v.x, v.y, v.z, v.w}; float x[8];
; #pragma unroll
;                 for (int e = 0; e < 4; ++e) { x[2 * e] = __uint_as_float(vv[e] << 16); x[2 * e + 1] = __uint_as_float(vv[e] & 0xffff0000u); }
;                 if (j < 4) { const f32x4 wa = *(const f32x4*)(gconv_w + j * CONVCH + col), wb = *(const f32x4*)(gconv_w + j * CONVCH + col + 4);
; #pragma unroll
;                     for (int e = 0; e < 8; ++e) y0[e] += (e < 4 ? wa[e] : wb[e - 4]) * x[e]; }
;                 if (j > 0) { const f32x4 wa = *(const f32x4*)(gconv_w + (j - 1) * CONVCH + col), wb = *(const f32x4*)(gconv_w + (j - 1) * CONVCH + col + 4);
; #pragma unroll
;                     for (int e = 0; e < 8; ++e) y1[e] += (e < 4 ? wa[e] : wb[e - 4]) * x[e]; } }
;             float s0 = 0.f, s1 = 0.f;
; #pragma unroll
;             for (int e = 0; e < 8; ++e) { y0[e] = silu_f(y0[e]); y1[e] = silu_f(y1[e]); s0 += y0[e] * y0[e]; s1 += y1[e] * y1[e]; }
;             if (part < 2) {
;                 s0 = row16_sum(s0); s1 = row16_sum(s1);
;                 float sc0 = rsqrtf(s0 + EPS), sc1 = rsqrtf(s1 + EPS); if (part == 0) { sc0 *= 0.08838834764831845f; sc1 *= 0.08838834764831845f; }
; #pragma unroll
;                 for (int e = 0; e < 8; ++e) { y0[e] *= sc0; y1[e] *= sc1; }
;                 LAS unsigned char* img = lds + (part == 0 ? P2_QN : P2_KN);
;                 u32x4 w0, w1; w0.x = cvt_pk_bf16(y0[0], y0[1]); w0.y = cvt_pk_bf16(y0[2], y0[3]); w0.z = cvt_pk_bf16(y0[4], y0[5]); w0.w = cvt_pk_bf16(y0[6], y0[7]);
;                 w1.x = cvt_pk_bf16(y1[0], y1[1]); w1.y = cvt_pk_bf16(y1[2], y1[3]); w1.z = cvt_pk_bf16(y1[4], y1[5]); w1.w = cvt_pk_bf16(y1[6], y1[7]);
;                 *(LAS u32x4*)(img + (i0 * 136 + 8 * cc) * 2) = w0; *(LAS u32x4*)(img + ((i0 + 1) * 136 + 8 * cc) * 2) = w1;
;                 if (part == 1) {
;                     const float f0 = be0 * eg0, f1 = be1 * eg1;
; #pragma unroll
;                     for (int e = 0; e < 8; ++e) *(LAS unsigned*)(lds + P2_KBT + ((8 * cc + e) * 72 + i0) * 2) = cvt_pk_bf16(y0[e] * f0, y1[e] * f1);
	v_pk_fma_f32 v[62:63], v[214:215], v[120:121], v[62:63] op_sel_hi:[0,1,1]
	v_pk_fma_f32 v[66:67], v[214:215], v[128:129], v[66:67] op_sel:[1,0,0]
	v_pk_fma_f32 v[54:55], v[58:59], v[54:55], 0 op_sel_hi:[0,1,0]
	v_pk_fma_f32 v[70:71], v[216:217], v[136:137], v[70:71] op_sel_hi:[0,1,1]
	v_mul_f32_e32 v58, 0xbfb8aa3b, v63
	v_mul_f32_e32 v68, 0xbfb8aa3b, v62
	v_mul_f32_e32 v72, 0xbfb8aa3b, v67
	v_mul_f32_e32 v74, 0xbfb8aa3b, v66
	v_mul_f32_e32 v75, 0xbfb8aa3b, v71
	v_exp_f32_e32 v58, v58
	v_exp_f32_e32 v68, v68
	v_exp_f32_e32 v72, v72
	v_exp_f32_e32 v74, v74
	v_exp_f32_e32 v75, v75
	v_add_f32_e32 v58, 1.0, v58
	v_add_f32_e32 v68, 1.0, v68
	v_add_f32_e32 v72, 1.0, v72
	v_add_f32_e32 v94, 1.0, v74
	v_add_f32_e32 v96, 1.0, v75
	v_rcp_f32_e32 v75, v58
	v_rcp_f32_e32 v74, v68
	v_rcp_f32_e32 v95, v72
	v_rcp_f32_e32 v94, v94
	v_and_b32_e32 v59, 0xffff0000, v59
	v_pk_mul_f32 v[62:63], v[62:63], v[74:75]
	v_mul_f32_e32 v76, 0xbfb8aa3b, v70
	v_pk_mul_f32 v[66:67], v[66:67], v[94:95]
	v_pk_mul_f32 v[62:63], v[36:37], v[62:63]
	v_pk_mul_f32 v[66:67], v[36:37], v[66:67]
	v_cvt_pk_bf16_f32 v58, v62, v63
	v_cvt_pk_bf16_f32 v62, v66, v67
	ds_write2_b32 v138, v58, v62 offset1:36
	v_mov_b32_e32 v62, v209
	v_pk_fma_f32 v[46:47], v[62:63], v[46:47], v[54:55] op_sel_hi:[0,1,1]
	v_mov_b32_e32 v54, v213
	v_mov_b32_e32 v58, v51
	v_pk_fma_f32 v[46:47], v[54:55], v[50:51], v[46:47] op_sel_hi:[0,1,1]
	v_mov_b32_e32 v50, v217
	v_pk_fma_f32 v[46:47], v[50:51], v[58:59], v[46:47] op_sel_hi:[0,1,1]
	v_mul_f32_e32 v50, 0xbfb8aa3b, v47
	v_exp_f32_e32 v50, v50
	v_mul_f32_e32 v51, 0xbfb8aa3b, v46
	v_exp_f32_e32 v54, v51
	v_exp_f32_e32 v76, v76
	v_add_f32_e32 v50, 1.0, v50
	v_rcp_f32_e32 v51, v50
	v_add_f32_e32 v50, 1.0, v54
	v_rcp_f32_e32 v50, v50
	v_add_f32_e32 v68, 1.0, v76
	v_rcp_f32_e32 v97, v96
	v_rcp_f32_e32 v96, v68
	v_pk_mul_f32 v[46:47], v[46:47], v[50:51]
	v_lshlrev_b32_e32 v51, 16, v52
	v_pk_mul_f32 v[46:47], v[36:37], v[46:47]
	v_pk_mul_f32 v[54:55], v[70:71], v[96:97]
	v_cvt_pk_bf16_f32 v63, v46, v47
	v_lshlrev_b32_e32 v47, 16, v56
	v_lshlrev_b32_e32 v46, 16, v48
	v_pk_mul_f32 v[54:55], v[36:37], v[54:55]
	v_mov_b32_e32 v50, v47
	v_pk_fma_f32 v[46:47], v[222:223], v[46:47], 0 op_sel_hi:[0,1,0]
	v_cvt_pk_bf16_f32 v62, v54, v55
	v_lshlrev_b32_e32 v55, 16, v64
	v_mov_b32_e32 v54, v51
	v_pk_fma_f32 v[46:47], v[226:227], v[50:51], v[46:47] op_sel_hi:[0,1,1]
	v_lshlrev_b32_e32 v59, 16, v60
	v_mov_b32_e32 v58, v55
	v_pk_fma_f32 v[46:47], v[230:231], v[54:55], v[46:47] op_sel_hi:[0,1,1]
	v_pk_fma_f32 v[46:47], v[234:235], v[58:59], v[46:47] op_sel_hi:[0,1,1]
	v_mul_f32_e32 v50, 0xbfb8aa3b, v47
	v_exp_f32_e32 v50, v50
	v_mul_f32_e32 v51, 0xbfb8aa3b, v46
	v_exp_f32_e32 v54, v51
	v_and_b32_e32 v55, 0xffff0000, v56
	v_add_f32_e32 v50, 1.0, v50
	v_rcp_f32_e32 v51, v50
	v_add_f32_e32 v50, 1.0, v54
	v_and_b32_e32 v54, 0xffff0000, v48
	v_and_b32_e32 v59, 0xffff0000, v52
	v_mov_b32_e32 v58, v55
	v_pk_fma_f32 v[54:55], v[222:223], v[54:55], 0 op_sel:[1,0,0] op_sel_hi:[1,1,0]
	ds_write2_b32 v138, v62, v63 offset0:72 offset1:108
	v_and_b32_e32 v63, 0xffff0000, v64
	v_mov_b32_e32 v62, v59
	v_pk_fma_f32 v[54:55], v[226:227], v[58:59], v[54:55] op_sel:[1,0,0]
	v_and_b32_e32 v67, 0xffff0000, v60
	v_mov_b32_e32 v66, v63
	v_pk_fma_f32 v[54:55], v[230:231], v[62:63], v[54:55] op_sel:[1,0,0]
	v_rcp_f32_e32 v50, v50
	v_pk_fma_f32 v[54:55], v[234:235], v[66:67], v[54:55] op_sel:[1,0,0]
	v_pk_mul_f32 v[46:47], v[46:47], v[50:51]
	v_mul_f32_e32 v48, 0xbfb8aa3b, v55
	v_exp_f32_e32 v48, v48
	v_mul_f32_e32 v52, 0xbfb8aa3b, v54
	v_exp_f32_e32 v52, v52
	v_pk_mul_f32 v[46:47], v[36:37], v[46:47]
	v_add_f32_e32 v48, 1.0, v48
	v_rcp_f32_e32 v59, v48
	v_add_f32_e32 v48, 1.0, v52
	v_rcp_f32_e32 v58, v48
	v_cvt_pk_bf16_f32 v48, v46, v47
	v_lshlrev_b32_e32 v51, 16, v53
	v_pk_mul_f32 v[46:47], v[54:55], v[58:59]
	s_nop 0
	v_pk_mul_f32 v[46:47], v[36:37], v[46:47]
	v_lshlrev_b32_e32 v55, 16, v65
	v_cvt_pk_bf16_f32 v52, v46, v47
	v_lshlrev_b32_e32 v46, 16, v49
	v_lshlrev_b32_e32 v47, 16, v57
	v_mov_b32_e32 v50, v47
	v_pk_fma_f32 v[46:47], v[224:225], v[46:47], 0 op_sel_hi:[0,1,0]
	v_mov_b32_e32 v54, v51
	v_pk_fma_f32 v[46:47], v[228:229], v[50:51], v[46:47] op_sel_hi:[0,1,1]
	v_lshlrev_b32_e32 v59, 16, v61
	v_mov_b32_e32 v58, v55
	v_pk_fma_f32 v[46:47], v[232:233], v[54:55], v[46:47] op_sel_hi:[0,1,1]
	v_pk_fma_f32 v[46:47], v[236:237], v[58:59], v[46:47] op_sel_hi:[0,1,1]
	v_mul_f32_e32 v50, 0xbfb8aa3b, v47
	v_exp_f32_e32 v50, v50
	v_mul_f32_e32 v51, 0xbfb8aa3b, v46
	v_exp_f32_e32 v54, v51
	ds_write2_b32 v138, v48, v52 offset0:144 offset1:180
	v_add_f32_e32 v48, 1.0, v50
	v_rcp_f32_e32 v51, v48
	v_add_f32_e32 v58, 1.0, v54
	v_and_b32_e32 v55, 0xffff0000, v57
	v_and_b32_e32 v54, 0xffff0000, v49
	v_mov_b32_e32 v50, v225
	v_and_b32_e32 v49, 0xffff0000, v53
	v_mov_b32_e32 v48, v55
	v_pk_fma_f32 v[54:55], v[50:51], v[54:55], 0 op_sel_hi:[0,1,0]
	v_mov_b32_e32 v50, v229
	v_and_b32_e32 v53, 0xffff0000, v65
	v_mov_b32_e32 v52, v49
	v_pk_fma_f32 v[48:49], v[50:51], v[48:49], v[54:55] op_sel_hi:[0,1,1]
	v_mov_b32_e32 v50, v233
	v_and_b32_e32 v57, 0xffff0000, v61
	v_mov_b32_e32 v56, v53
	v_pk_fma_f32 v[48:49], v[50:51], v[52:53], v[48:49] op_sel_hi:[0,1,1]
	v_mov_b32_e32 v50, v237
	v_pk_fma_f32 v[48:49], v[50:51], v[56:57], v[48:49] op_sel_hi:[0,1,1]
	v_mul_f32_e32 v50, 0xbfb8aa3b, v49
	v_exp_f32_e32 v52, v50
	v_mul_f32_e32 v50, 0xbfb8aa3b, v48
	v_exp_f32_e32 v54, v50
	v_rcp_f32_e32 v50, v58
	v_add_f32_e32 v52, 1.0, v52
	v_rcp_f32_e32 v53, v52
	v_add_f32_e32 v52, 1.0, v54
	v_rcp_f32_e32 v52, v52
	v_pk_mul_f32 v[46:47], v[46:47], v[50:51]
	s_nop 0
	v_pk_mul_f32 v[46:47], v[36:37], v[46:47]
	s_nop 0
	v_cvt_pk_bf16_f32 v50, v46, v47
	v_pk_mul_f32 v[46:47], v[48:49], v[52:53]
	s_nop 0
	v_pk_mul_f32 v[36:37], v[36:37], v[46:47]
	s_nop 0
	v_cvt_pk_bf16_f32 v36, v36, v37
	ds_write2_b32 v138, v50, v36 offset0:216 offset1:252
	s_cmp_gt_i32 s14, -1
	v_lshlrev_b32_e32 v54, 4, v116
	s_cbranch_scc0 .LBB0_508
	s_lshr_b32 s0, s14, 3
	s_mul_hi_u32 s1, s0, 0x1f07c1f1
	s_lshr_b32 s1, s1, 2
	s_mul_i32 s1, s1, 33
	s_and_b32 s34, s14, 7
	s_sub_i32 s0, s0, s1
	s_mul_hi_u32 s1, s14, 0x3e0f83e1
	s_lshr_b32 s14, s1, 6
	s_lshl_b32 s35, s0, 6
	s_lshl_b32 s0, s34, 8
	s_add_u32 s0, s88, s0
	s_addc_u32 s1, s89, 0
	v_and_b32_e32 v2, 0xf0, v54
	v_mov_b32_e32 v3, v34
	v_mov_b32_e32 v4, v34
	v_mov_b32_e32 v5, v34
	v_add_u32_e32 v18, s35, v119
	s_mulk_i32 s14, 0x810
	v_lshl_add_u64 v[46:47], s[0:1], 0, v[2:3]
	v_mov_b32_e32 v2, v34
	v_mov_b64_e32 v[8:9], v[4:5]
	v_cmp_lt_i32_e32 vcc, -1, v18
	v_add_u32_e32 v26, s14, v18
	v_mov_b64_e32 v[6:7], v[2:3]
	s_and_saveexec_b64 s[0:1], vcc
	s_cbranch_execz .LBB0_485
	v_mad_u64_u32 v[6:7], s[4:5], v26, s2, v[46:47]
	global_load_dwordx4 v[6:9], v[6:7], off
